# v55 + P0 tail rebalance: c1 dot products moved to waves gw>=1536 (one transpose item fewer), T5 LUT to waves 1000-1063
# baseline (speedup 1.0000x reference)
.LBB0_118:
	s_add_u32 s18, s74, 0x8000000
	s_addc_u32 s19, s75, 0
	s_add_u32 s24, s74, 0x8000400
	s_addc_u32 s25, s75, 0
	s_cmpk_lt_i32 s78, 0x600
	s_cbranch_scc1 .LBB0_129
	v_mbcnt_hi_u32_b32 v2, -1, v208
	v_and_b32_e32 v3, 64, v2
	v_add_u32_e32 v3, 64, v3
	v_xor_b32_e32 v4, 1, v2
	v_cmp_lt_i32_e64 s[4:5], v4, v3
	v_add_u32_e32 v6, 0x140, v194
	v_add_u32_e32 v8, 0x100, v194
	v_cndmask_b32_e64 v4, v2, v4, s[4:5]
	v_lshlrev_b32_e32 v46, 2, v4
	v_xor_b32_e32 v4, 2, v2
	v_cmp_lt_i32_e64 s[4:5], v4, v3
	v_add_u32_e32 v10, 0xc0, v194
	v_add_u32_e32 v12, 0x80, v194
	v_cndmask_b32_e64 v4, v2, v4, s[4:5]
	v_lshlrev_b32_e32 v47, 2, v4
	v_xor_b32_e32 v4, 4, v2
	v_cmp_lt_i32_e64 s[4:5], v4, v3
	v_add_u32_e32 v14, 64, v194
	s_movk_i32 s2, 0x1000
	v_cndmask_b32_e64 v4, v2, v4, s[4:5]
	v_lshlrev_b32_e32 v48, 2, v4
	v_xor_b32_e32 v4, 8, v2
	v_cmp_lt_i32_e64 s[4:5], v4, v3
	v_ashrrev_i32_e32 v7, 31, v6
	v_ashrrev_i32_e32 v9, 31, v8
	v_cndmask_b32_e64 v4, v2, v4, s[4:5]
	v_lshlrev_b32_e32 v49, 2, v4
	v_xor_b32_e32 v4, 16, v2
	v_cmp_lt_i32_e64 s[4:5], v4, v3
	v_ashrrev_i32_e32 v11, 31, v10
	v_ashrrev_i32_e32 v13, 31, v12
	v_cndmask_b32_e64 v4, v2, v4, s[4:5]
	v_lshlrev_b32_e32 v50, 2, v4
	v_xor_b32_e32 v4, 32, v2
	v_cmp_lt_i32_e64 s[4:5], v4, v3
	v_ashrrev_i32_e32 v15, 31, v14
	v_mov_b64_e32 v[16:17], 0x700
	v_cndmask_b32_e64 v2, v2, v4, s[4:5]
	v_lshlrev_b32_e32 v51, 2, v2
	v_add_u32_e32 v2, 0x1c0, v194
	v_add_u32_e32 v4, 0x180, v194
	v_ashrrev_i32_e32 v3, 31, v2
	v_ashrrev_i32_e32 v5, 31, v4
	v_cmp_gt_i32_e32 vcc, s2, v194
	s_mov_b32 s27, 0
	v_cmp_eq_u32_e64 s[4:5], 0, v194
	v_add_u32_e32 v52, 0xfffffe00, v194
	s_sub_i32 s33, 0x7ff, s78
	v_lshlrev_b64 v[2:3], 9, v[2:3]
	v_lshlrev_b64 v[4:5], 9, v[4:5]
	v_lshlrev_b64 v[6:7], 9, v[6:7]
	v_lshlrev_b64 v[8:9], 9, v[8:9]
	v_lshlrev_b64 v[10:11], 9, v[10:11]
	v_lshlrev_b64 v[12:13], 9, v[12:13]
	v_lshlrev_b64 v[14:15], 9, v[14:15]
	v_lshl_add_u64 v[16:17], v[194:195], 2, v[16:17]
	v_lshlrev_b64 v[18:19], 9, v[194:195]
	s_mov_b64 s[28:29], 0x40000
	s_mov_b64 s[30:31], 0x800
	s_movk_i32 s40, 0xdff
	s_sub_i32 s41, 0x7ff, s78
	s_branch .LBB0_121

.LBB0_129:
	s_add_i32 s2, s78, 0xfffffc18
	v_lshl_add_u32 v2, s2, 6, v194
	s_movk_i32 s2, 0x1000
	v_cmp_gt_u32_e32 vcc, s2, v2
	s_and_saveexec_b64 s[4:5], vcc
	s_cbranch_execz .LBB0_134
	s_lshl_b32 s2, s92, 9
	v_ashrrev_i32_e32 v3, 31, v2
	v_lshl_add_u64 v[4:5], v[2:3], 2, s[74:75]
	s_mov_b64 s[6:7], 0x8001000
	s_ashr_i32 s3, s2, 31
	v_lshl_add_u64 v[4:5], v[4:5], 0, s[6:7]
	s_lshl_b64 s[6:7], s[2:3], 2
	s_mov_b64 s[26:27], 0
	s_mov_b32 s3, 0x800000
	s_mov_b32 s30, 0x3f317217
	s_mov_b32 s31, 0x7f800000
	s_mov_b32 s33, 0x40051592
	s_movk_i32 s34, 0xfff
	v_mov_b32_e32 v3, 0x41b17218
	s_branch .LBB0_132
